# combined v32 plus P0 weight-copy loop: wait for next item loads moved from start of LDS transpose to end of iteration (vmcnt(4))
# speedup vs baseline: 1.0037x; 1.0000x over previous
.LBB0_104:
	s_or_b64 exec, exec, s[4:5]
	s_mulk_i32 s28, 0x2100
	s_add_i32 s4, s28, 0
	v_and_b32_e32 v33, 7, v79
	s_movk_i32 s5, 0x84
	v_lshl_add_u32 v34, v33, 4, s4
	v_mul_lo_u32 v35, v74, s5
	v_lshlrev_b32_e32 v32, 3, v33
	v_mul_u32_u24_e32 v33, 0x420, v33
	v_lshlrev_b32_e32 v36, 2, v74
	s_lshl_b32 s40, s35, 3
	s_mov_b32 s13, 0
	v_add_u32_e32 v75, 8, v74
	v_add_u32_e32 v76, 16, v74
	v_add_u32_e32 v77, 24, v74
	v_add_u32_e32 v78, 32, v74
	v_add_u32_e32 v79, 40, v74
	v_add3_u32 v80, s4, v33, v36
	s_movk_i32 s41, 0x9ff
	s_movk_i32 s42, 0x1017
	v_add_u32_e32 v81, v34, v35
	v_lshlrev_b32_e32 v70, 1, v32
	s_waitcnt vmcnt(0)
	s_branch .LBB0_106

.LBB0_162:
	v_add_u32_e32 v68, 0x420, v81
	ds_write2_b32 v81, v67, v1 offset1:1
	ds_write2_b32 v81, v2, v3 offset0:2 offset1:3
	ds_write2_b32 v68, v4, v5 offset1:1
	v_add_u32_e32 v68, 0x428, v81
	ds_write2_b32 v68, v6, v7 offset1:1
	v_add_u32_e32 v68, 0x840, v81
	ds_write2_b32 v68, v8, v9 offset1:1
	v_add_u32_e32 v68, 0x848, v81
	ds_write2_b32 v68, v10, v11 offset1:1
	v_add_u32_e32 v68, 0xc60, v81
	ds_write2_b32 v68, v12, v13 offset1:1
	v_add_u32_e32 v68, 0xc68, v81
	ds_write2_b32 v68, v14, v15 offset1:1
	v_add_u32_e32 v68, 0x1080, v81
	ds_write2_b32 v68, v16, v17 offset1:1
	v_add_u32_e32 v68, 0x1088, v81
	ds_write2_b32 v68, v18, v19 offset1:1
	v_add_u32_e32 v68, 0x14a0, v81
	ds_write2_b32 v68, v20, v21 offset1:1
	v_add_u32_e32 v68, 0x14a8, v81
	ds_write2_b32 v68, v22, v23 offset1:1
	v_add_u32_e32 v68, 0x18c0, v81
	ds_write2_b32 v68, v24, v25 offset1:1
	v_add_u32_e32 v68, 0x18c8, v81
	ds_write2_b32 v68, v26, v27 offset1:1
	v_add_u32_e32 v68, 0x1ce0, v81
	ds_write2_b32 v68, v28, v29 offset1:1
	v_add_u32_e32 v68, 0x1ce8, v81
	ds_write2_b32 v68, v30, v31 offset1:1
	v_add_u32_e32 v68, s38, v74
	v_mad_u64_u32 v[100:101], s[18:19], v68, s39, 0
	s_waitcnt lgkmcnt(0)
	v_ashrrev_i32_e32 v71, 31, v68
	v_mov_b32_e32 v68, v101
	ds_read2_b32 v[72:73], v80 offset0:33 offset1:41
	ds_read2_b32 v[86:87], v80 offset1:8
	ds_read2_b32 v[88:89], v80 offset0:66 offset1:74
	ds_read2_b32 v[90:91], v80 offset0:99 offset1:107
	ds_read2_b32 v[92:93], v80 offset0:132 offset1:140
	ds_read2_b32 v[94:95], v80 offset0:165 offset1:173
	ds_read2_b32 v[96:97], v80 offset0:198 offset1:206
	ds_read2_b32 v[98:99], v80 offset0:231 offset1:239
	v_mad_u64_u32 v[102:103], s[18:19], v71, s39, v[68:69]
	v_mov_b32_e32 v101, v102
	v_lshl_add_u64 v[100:101], v[100:101], 1, s[6:7]
	s_lshl_b64 s[18:19], s[12:13], 1
	s_ashr_i32 s11, s10, 31
	v_lshl_add_u64 v[100:101], v[100:101], 0, s[18:19]
	s_lshl_b64 s[20:21], s[10:11], 1
	v_lshl_add_u64 v[100:101], v[100:101], 0, s[20:21]
	v_mov_b32_e32 v71, v69
	s_waitcnt lgkmcnt(6)
	v_cvt_pk_bf16_f32 v82, v86, v72
	s_waitcnt lgkmcnt(4)
	v_cvt_pk_bf16_f32 v83, v88, v90
	s_waitcnt lgkmcnt(2)
	v_cvt_pk_bf16_f32 v84, v92, v94
	s_waitcnt lgkmcnt(0)
	v_cvt_pk_bf16_f32 v85, v96, v98
	v_lshl_add_u64 v[100:101], v[100:101], 0, v[70:71]
	v_add_u32_e32 v68, s38, v75
	global_store_dwordx4 v[100:101], v[82:85], off
	v_ashrrev_i32_e32 v86, 31, v68
	s_andn2_b64 vcc, exec, s[14:15]
	v_cvt_pk_bf16_f32 v82, v87, v73
	v_mad_u64_u32 v[72:73], s[22:23], v68, s39, 0
	v_mov_b32_e32 v68, v73
	v_mad_u64_u32 v[86:87], s[22:23], v86, s39, v[68:69]
	v_mov_b32_e32 v73, v86
	v_lshl_add_u64 v[72:73], v[72:73], 1, s[6:7]
	v_lshl_add_u64 v[72:73], v[72:73], 0, s[18:19]
	v_lshl_add_u64 v[72:73], v[72:73], 0, s[20:21]
	v_cvt_pk_bf16_f32 v83, v89, v91
	v_cvt_pk_bf16_f32 v84, v93, v95
	v_cvt_pk_bf16_f32 v85, v97, v99
	v_lshl_add_u64 v[72:73], v[72:73], 0, v[70:71]
	v_add_u32_e32 v68, s38, v76
	ds_read2_b32 v[86:87], v80 offset0:16 offset1:24
	ds_read2_b32 v[88:89], v80 offset0:49 offset1:57
	ds_read2_b32 v[90:91], v80 offset0:82 offset1:90
	ds_read2_b32 v[92:93], v80 offset0:115 offset1:123
	ds_read2_b32 v[94:95], v80 offset0:148 offset1:156
	ds_read2_b32 v[96:97], v80 offset0:181 offset1:189
	ds_read2_b32 v[98:99], v80 offset0:214 offset1:222
	ds_read2_b32 v[100:101], v80 offset0:247 offset1:255
	global_store_dwordx4 v[72:73], v[82:85], off
	v_mad_u64_u32 v[72:73], s[22:23], v68, s39, 0
	s_waitcnt lgkmcnt(6)
	v_cvt_pk_bf16_f32 v82, v86, v88
	v_ashrrev_i32_e32 v86, 31, v68
	v_mov_b32_e32 v68, v73
	v_mad_u64_u32 v[102:103], s[22:23], v86, s39, v[68:69]
	v_mov_b32_e32 v73, v102
	v_lshl_add_u64 v[72:73], v[72:73], 1, s[6:7]
	v_lshl_add_u64 v[72:73], v[72:73], 0, s[18:19]
	v_lshl_add_u64 v[72:73], v[72:73], 0, s[20:21]
	s_waitcnt lgkmcnt(4)
	v_cvt_pk_bf16_f32 v83, v90, v92
	s_waitcnt lgkmcnt(2)
	v_cvt_pk_bf16_f32 v84, v94, v96
	s_waitcnt lgkmcnt(0)
	v_cvt_pk_bf16_f32 v85, v98, v100
	v_lshl_add_u64 v[72:73], v[72:73], 0, v[70:71]
	v_add_u32_e32 v68, s38, v77
	global_store_dwordx4 v[72:73], v[82:85], off
	v_mad_u64_u32 v[72:73], s[22:23], v68, s39, 0
	v_ashrrev_i32_e32 v86, 31, v68
	v_mov_b32_e32 v68, v73
	v_cvt_pk_bf16_f32 v82, v87, v89
	v_mad_u64_u32 v[86:87], s[22:23], v86, s39, v[68:69]
	v_mov_b32_e32 v73, v86
	v_lshl_add_u64 v[72:73], v[72:73], 1, s[6:7]
	v_lshl_add_u64 v[72:73], v[72:73], 0, s[18:19]
	v_lshl_add_u64 v[72:73], v[72:73], 0, s[20:21]
	v_cvt_pk_bf16_f32 v83, v91, v93
	v_cvt_pk_bf16_f32 v84, v95, v97
	v_cvt_pk_bf16_f32 v85, v99, v101
	v_lshl_add_u64 v[72:73], v[72:73], 0, v[70:71]
	global_store_dwordx4 v[72:73], v[82:85], off
	s_waitcnt lgkmcnt(0)
	s_cbranch_vccnz .LBB0_105
	s_mov_b32 s10, s45
	s_mov_b32 s39, s46
	s_mov_b64 s[6:7], s[16:17]
	s_mov_b32 s38, s44
	s_mov_b32 s12, s47
	s_mov_b32 s34, s43
	s_waitcnt vmcnt(4)
	v_mov_b32_e32 v67, v36
	v_mov_b32_e32 v1, v37
	v_mov_b32_e32 v2, v38
	v_mov_b32_e32 v3, v39
	v_mov_b32_e32 v4, v40
	v_mov_b32_e32 v5, v41
	v_mov_b32_e32 v6, v42
	v_mov_b32_e32 v7, v43
	v_mov_b32_e32 v8, v32
	v_mov_b32_e32 v9, v33
	v_mov_b32_e32 v10, v34
	v_mov_b32_e32 v11, v35
	v_mov_b32_e32 v12, v44
	v_mov_b32_e32 v13, v45
	v_mov_b32_e32 v14, v46
	v_mov_b32_e32 v15, v47
	v_mov_b32_e32 v16, v52
	v_mov_b32_e32 v17, v53
	v_mov_b32_e32 v18, v54
	v_mov_b32_e32 v19, v55
	v_mov_b32_e32 v20, v56
	v_mov_b32_e32 v21, v57
	v_mov_b32_e32 v22, v58
	v_mov_b32_e32 v23, v59
	v_mov_b32_e32 v24, v48
	v_mov_b32_e32 v25, v49
	v_mov_b32_e32 v26, v50
	v_mov_b32_e32 v27, v51
	v_mov_b32_e32 v28, v60
	v_mov_b32_e32 v29, v61
	v_mov_b32_e32 v30, v62
	v_mov_b32_e32 v31, v63
	s_branch .LBB0_105
